# layer-1 weight-conversion tiles (done in layer 0's mixer tail) assigned only to the 256 item blocks with the lighter lists, so the two-prompt-chain blocks are not extended
# speedup vs baseline: 1.0049x; 1.0049x over previous
.LBB0_1139:
	v_readlane_b32 s0, v205, 18
	v_readlane_b32 s1, v205, 19
	s_andn2_b64 vcc, exec, s[0:1]
	s_cbranch_vccnz .LBB0_1232
	v_readlane_b32 s2, v209, 0
	s_nop 3
	s_cmpk_lt_u32 s2, 0x100
	s_cbranch_scc1 .LBB0_1232
	s_sub_i32 s2, s2, 0x100
	s_branch .LBB0_1142
.LBB0_1141:
	s_movk_i32 s0, 0x100
	s_add_i32 s2, s0, s2
	s_cmpk_gt_i32 s2, 0x45f
	s_waitcnt lgkmcnt(0)
	s_cbranch_scc1 .LBB0_1232
